# stack on ovfinal: hand-written out-GEMM epilogue + batched/wide-store attention pass-1 epilogue + counted lgkmcnt in attention PV segments
# speedup vs baseline: 1.0077x; 1.0019x over previous
.LBB0_345:
	s_or_b64 exec, exec, s[2:3]
	v_add_u32_e32 v177, s54, v181
	v_add_f32_e32 v176, v176, v219
	ds_read_b64_tr_b16 v[196:197], v177 offset:0
	ds_read_b64_tr_b16 v[198:199], v177 offset:0x800
	ds_read_b64_tr_b16 v[200:201], v177 offset:0x1000
	ds_read_b64_tr_b16 v[202:203], v177 offset:0x1800
	ds_read_b64_tr_b16 v[206:207], v177 offset:0x2000
	ds_read_b64_tr_b16 v[208:209], v177 offset:0x2800
	ds_read_b64_tr_b16 v[210:211], v177 offset:0x3000
	ds_read_b64_tr_b16 v[212:213], v177 offset:0x3800
	v_add_f32_e32 v176, v176, v98
	s_waitcnt lgkmcnt(6)
	v_mfma_f32_32x32x16_bf16 v[50:65], v[150:153], v[196:199], v[50:65]
	v_exp_f32_e32 v195, v66
	v_exp_f32_e32 v196, v67
	ds_read_b64_tr_b16 v[66:67], v177 offset:0x200
	v_exp_f32_e32 v197, v68
	v_exp_f32_e32 v198, v69
	ds_read_b64_tr_b16 v[68:69], v177 offset:0xa00
	v_exp_f32_e32 v199, v82
	s_waitcnt lgkmcnt(6)
	v_mfma_f32_32x32x16_bf16 v[50:65], v[134:137], v[200:203], v[50:65]
	v_exp_f32_e32 v201, v83
	ds_read_b64_tr_b16 v[82:83], v177 offset:0x1200
	v_exp_f32_e32 v202, v84
	v_exp_f32_e32 v205, v85
	ds_read_b64_tr_b16 v[84:85], v177 offset:0x1a00
	ds_read_b64_tr_b16 v[214:215], v177 offset:0x2200
	ds_read_b64_tr_b16 v[216:217], v177 offset:0x2a00
	s_waitcnt lgkmcnt(8)
	v_mfma_f32_32x32x16_bf16 v[50:65], v[130:133], v[206:209], v[50:65]
	ds_read_b64_tr_b16 v[218:219], v177 offset:0x3200
	ds_read_b64_tr_b16 v[220:221], v177 offset:0x3a00
	s_waitcnt lgkmcnt(8)
	v_mfma_f32_32x32x16_bf16 v[50:65], v[126:129], v[210:213], v[50:65]
	s_waitcnt lgkmcnt(6)
	v_mfma_f32_32x32x16_bf16 v[34:49], v[150:153], v[66:69], v[34:49]
	ds_read_b64_tr_b16 v[66:67], v177 offset:0x400
	ds_read_b64_tr_b16 v[68:69], v177 offset:0xc00
	v_exp_f32_e32 v200, v70
	v_exp_f32_e32 v203, v71
	ds_read_b64_tr_b16 v[70:71], v177 offset:0x1400
	v_exp_f32_e32 v204, v72
	v_exp_f32_e32 v206, v73
	s_waitcnt lgkmcnt(7)
	v_mfma_f32_32x32x16_bf16 v[34:49], v[134:137], v[82:85], v[34:49]
	ds_read_b64_tr_b16 v[72:73], v177 offset:0x1c00
	ds_read_b64_tr_b16 v[82:83], v177 offset:0x2400
	ds_read_b64_tr_b16 v[84:85], v177 offset:0x2c00
	v_exp_f32_e32 v207, v86
	v_exp_f32_e32 v209, v87
	ds_read_b64_tr_b16 v[86:87], v177 offset:0x3400
	v_exp_f32_e32 v211, v88
	s_waitcnt lgkmcnt(9)
	v_mfma_f32_32x32x16_bf16 v[34:49], v[130:133], v[214:217], v[34:49]
	v_exp_f32_e32 v213, v89
	ds_read_b64_tr_b16 v[88:89], v177 offset:0x3c00
	s_waitcnt lgkmcnt(8)
	v_mfma_f32_32x32x16_bf16 v[34:49], v[126:129], v[218:221], v[34:49]
	s_waitcnt lgkmcnt(6)
	v_mfma_f32_32x32x16_bf16 v[18:33], v[150:153], v[66:69], v[18:33]
	ds_read_b64_tr_b16 v[66:67], v177 offset:0x600
	ds_read_b64_tr_b16 v[68:69], v177 offset:0xe00
	v_exp_f32_e32 v208, v74
	v_exp_f32_e32 v210, v75
	v_exp_f32_e32 v212, v76
	v_exp_f32_e32 v214, v77
	v_exp_f32_e32 v215, v90
	s_waitcnt lgkmcnt(6)
	v_mfma_f32_32x32x16_bf16 v[18:33], v[134:137], v[70:73], v[18:33]
	ds_read_b64_tr_b16 v[70:71], v177 offset:0x1600
	ds_read_b64_tr_b16 v[72:73], v177 offset:0x1e00
	ds_read_b64_tr_b16 v[74:75], v177 offset:0x2600
	ds_read_b64_tr_b16 v[76:77], v177 offset:0x2e00
	v_exp_f32_e32 v216, v91
	v_exp_f32_e32 v217, v92
	v_exp_f32_e32 v218, v93
	s_waitcnt lgkmcnt(8)
	v_mfma_f32_32x32x16_bf16 v[18:33], v[130:133], v[82:85], v[18:33]
	ds_read_b64_tr_b16 v[82:83], v177 offset:0x3600
	ds_read_b64_tr_b16 v[84:85], v177 offset:0x3e00
	s_waitcnt lgkmcnt(8)
	v_mfma_f32_32x32x16_bf16 v[18:33], v[126:129], v[86:89], v[18:33]
	s_waitcnt lgkmcnt(6)
	v_mfma_f32_32x32x16_bf16 v[2:17], v[150:153], v[66:69], v[2:17]
	v_exp_f32_e32 v221, v94
	v_exp_f32_e32 v150, v78
	v_exp_f32_e32 v222, v95
	v_exp_f32_e32 v151, v79
	v_exp_f32_e32 v223, v96
	v_exp_f32_e32 v152, v80
	v_exp_f32_e32 v224, v97
	s_waitcnt lgkmcnt(4)
	v_mfma_f32_32x32x16_bf16 v[2:17], v[134:137], v[70:73], v[2:17]
	v_exp_f32_e32 v153, v81
	v_add_u32_e32 v182, s56, v183
	s_add_i32 s83, s83, 2
	v_add_u32_e32 v194, 0x200, v194
	s_waitcnt lgkmcnt(2)
	v_mfma_f32_32x32x16_bf16 v[2:17], v[130:133], v[74:77], v[2:17]
	s_waitcnt vmcnt(0)
	ds_write_b128 v235, v[142:145] offset:49152
	ds_write_b128 v182, v[138:141]
	ds_write_b128 v182, v[154:157] offset:8192
	s_mov_b32 s80, s54
	s_mov_b32 s54, s55
	s_mov_b32 s55, s56
	s_mov_b32 s56, s80
	s_cmp_ge_u32 s83, s78
	s_waitcnt lgkmcnt(0)
	s_barrier
	v_mfma_f32_32x32x16_bf16 v[2:17], v[126:129], v[82:85], v[2:17]
	s_cbranch_scc1 .LBB0_350

.LBB0_348:
	s_or_b64 exec, exec, s[2:3]
	v_add_u32_e32 v180, s54, v181
	ds_read_b64_tr_b16 v[196:197], v180 offset:0
	ds_read_b64_tr_b16 v[198:199], v180 offset:0x800
	ds_read_b64_tr_b16 v[200:201], v180 offset:0x1000
	ds_read_b64_tr_b16 v[202:203], v180 offset:0x1800
	ds_read_b64_tr_b16 v[204:205], v180 offset:0x2000
	ds_read_b64_tr_b16 v[206:207], v180 offset:0x2800
	ds_read_b64_tr_b16 v[208:209], v180 offset:0x3000
	ds_read_b64_tr_b16 v[210:211], v180 offset:0x3800
	s_addk_i32 s82, 0x80
	s_waitcnt lgkmcnt(6)
	v_mfma_f32_32x32x16_bf16 v[50:65], v[134:137], v[196:199], v[50:65]
	v_exp_f32_e32 v213, v66
	v_exp_f32_e32 v215, v67
	ds_read_b64_tr_b16 v[66:67], v180 offset:0x200
	v_exp_f32_e32 v217, v68
	v_exp_f32_e32 v221, v69
	ds_read_b64_tr_b16 v[68:69], v180 offset:0xa00
	v_exp_f32_e32 v212, v82
	s_waitcnt lgkmcnt(6)
	v_mfma_f32_32x32x16_bf16 v[50:65], v[138:141], v[200:203], v[50:65]
	v_exp_f32_e32 v214, v83
	ds_read_b64_tr_b16 v[82:83], v180 offset:0x1200
	v_exp_f32_e32 v216, v84
	v_exp_f32_e32 v218, v85
	ds_read_b64_tr_b16 v[84:85], v180 offset:0x1a00
	ds_read_b64_tr_b16 v[196:197], v180 offset:0x2200
	ds_read_b64_tr_b16 v[198:199], v180 offset:0x2a00
	s_waitcnt lgkmcnt(8)
	v_mfma_f32_32x32x16_bf16 v[50:65], v[126:129], v[204:207], v[50:65]
	ds_read_b64_tr_b16 v[200:201], v180 offset:0x3200
	ds_read_b64_tr_b16 v[202:203], v180 offset:0x3a00
	s_waitcnt lgkmcnt(8)
	v_mfma_f32_32x32x16_bf16 v[50:65], v[130:133], v[208:211], v[50:65]
	s_waitcnt lgkmcnt(6)
	v_mfma_f32_32x32x16_bf16 v[34:49], v[134:137], v[66:69], v[34:49]
	ds_read_b64_tr_b16 v[66:67], v180 offset:0x400
	ds_read_b64_tr_b16 v[68:69], v180 offset:0xc00
	v_exp_f32_e32 v205, v70
	v_exp_f32_e32 v207, v71
	ds_read_b64_tr_b16 v[70:71], v180 offset:0x1400
	v_exp_f32_e32 v209, v72
	v_exp_f32_e32 v211, v73
	s_waitcnt lgkmcnt(7)
	v_mfma_f32_32x32x16_bf16 v[34:49], v[138:141], v[82:85], v[34:49]
	ds_read_b64_tr_b16 v[72:73], v180 offset:0x1c00
	ds_read_b64_tr_b16 v[82:83], v180 offset:0x2400
	ds_read_b64_tr_b16 v[84:85], v180 offset:0x2c00
	v_exp_f32_e32 v204, v86
	v_exp_f32_e32 v206, v87
	ds_read_b64_tr_b16 v[86:87], v180 offset:0x3400
	v_exp_f32_e32 v208, v88
	s_waitcnt lgkmcnt(9)
	v_mfma_f32_32x32x16_bf16 v[34:49], v[126:129], v[196:199], v[34:49]
	v_exp_f32_e32 v210, v89
	ds_read_b64_tr_b16 v[88:89], v180 offset:0x3c00
	s_waitcnt lgkmcnt(8)
	v_mfma_f32_32x32x16_bf16 v[34:49], v[130:133], v[200:203], v[34:49]
	s_waitcnt lgkmcnt(6)
	v_mfma_f32_32x32x16_bf16 v[18:33], v[134:137], v[66:69], v[18:33]
	ds_read_b64_tr_b16 v[66:67], v180 offset:0x600
	ds_read_b64_tr_b16 v[68:69], v180 offset:0xe00
	v_exp_f32_e32 v197, v74
	v_exp_f32_e32 v199, v75
	v_exp_f32_e32 v201, v76
	v_exp_f32_e32 v203, v77
	v_exp_f32_e32 v196, v90
	s_waitcnt lgkmcnt(6)
	v_mfma_f32_32x32x16_bf16 v[18:33], v[138:141], v[70:73], v[18:33]
	ds_read_b64_tr_b16 v[70:71], v180 offset:0x1600
	ds_read_b64_tr_b16 v[72:73], v180 offset:0x1e00
	ds_read_b64_tr_b16 v[74:75], v180 offset:0x2600
	ds_read_b64_tr_b16 v[76:77], v180 offset:0x2e00
	v_exp_f32_e32 v198, v91
	v_exp_f32_e32 v200, v92
	v_exp_f32_e32 v202, v93
	s_waitcnt lgkmcnt(8)
	v_mfma_f32_32x32x16_bf16 v[18:33], v[126:129], v[82:85], v[18:33]
	ds_read_b64_tr_b16 v[82:83], v180 offset:0x3600
	ds_read_b64_tr_b16 v[84:85], v180 offset:0x3e00
	s_waitcnt lgkmcnt(8)
	v_mfma_f32_32x32x16_bf16 v[18:33], v[130:133], v[86:89], v[18:33]
	s_waitcnt lgkmcnt(6)
	v_mfma_f32_32x32x16_bf16 v[2:17], v[134:137], v[66:69], v[2:17]
	v_add_u32_e32 v182, s56, v183
	v_exp_f32_e32 v222, v94
	v_exp_f32_e32 v223, v78
	v_exp_f32_e32 v224, v95
	s_waitcnt lgkmcnt(4)
	v_mfma_f32_32x32x16_bf16 v[2:17], v[138:141], v[70:73], v[2:17]
	v_exp_f32_e32 v226, v79
	v_exp_f32_e32 v227, v96
	v_exp_f32_e32 v228, v80
	v_exp_f32_e32 v229, v97
	v_exp_f32_e32 v230, v81
	s_waitcnt vmcnt(0)
	ds_write_b128 v235, v[146:149] offset:32768
	ds_write_b128 v182, v[142:145]
	ds_write_b128 v182, v[154:157] offset:8192
	s_waitcnt lgkmcnt(0)
	v_mfma_f32_32x32x16_bf16 v[2:17], v[126:129], v[74:77], v[2:17]
	s_barrier
	v_mfma_f32_32x32x16_bf16 v[2:17], v[130:133], v[82:85], v[2:17]
	s_mov_b32 s80, s54
	s_mov_b32 s54, s55
	s_mov_b32 s55, s56
	s_mov_b32 s56, s80
	s_cmp_eq_u32 s82, s99
	s_cbranch_scc1 .Lattn_refill_b

.LBB0_356:
	v_mov_b32_e32 v218, v68
	v_mov_b32_e32 v216, v163
	v_ashrrev_i32_e32 v217, 31, v163
	v_lshl_add_u64 v[216:217], v[216:217], 2, s[38:39]
	global_load_dword v204, v[216:217], off
	global_load_dword v205, v[216:217], off offset:128
	global_load_dword v206, v[216:217], off offset:256
	global_load_dword v207, v[216:217], off offset:384
	global_load_dwordx4 v[106:109], v[158:159], off
	global_load_dwordx4 v[110:113], v[158:159], off offset:16
	global_load_dwordx4 v[114:117], v[158:159], off offset:32
	global_load_dwordx4 v[118:121], v[158:159], off offset:48
	global_load_dwordx4 v[122:125], v[158:159], off offset:64
	global_load_dwordx4 v[126:129], v[158:159], off offset:80
	global_load_dwordx4 v[130:133], v[158:159], off offset:96
	global_load_dwordx4 v[134:137], v[158:159], off offset:112
	global_load_dwordx4 v[138:141], v[158:159], off offset:128
	global_load_dwordx4 v[142:145], v[158:159], off offset:144
	global_load_dwordx4 v[146:149], v[158:159], off offset:160
	global_load_dwordx4 v[150:153], v[158:159], off offset:176
	global_load_dwordx4 v[154:157], v[158:159], off offset:192
	global_load_dwordx4 v[176:179], v[158:159], off offset:208
	global_load_dwordx4 v[180:183], v[158:159], off offset:224
	global_load_dwordx4 v[184:187], v[158:159], off offset:240
	ds_read_b128 v[66:69], v218
	ds_read_b128 v[70:73], v218 offset:32
	ds_read_b128 v[74:77], v218 offset:64
	ds_read_b128 v[78:81], v218 offset:96
	s_add_u32 s100, s92, s20
	s_addc_u32 s101, s93, s21
	s_add_u32 s100, s100, 0x2e400000
	s_addc_u32 s101, s101, 0
	v_xor_b32_e32 v208, 16, v174
	v_lshlrev_b32_e32 v208, 2, v208
	s_waitcnt lgkmcnt(0)
	v_rcp_f32_e32 v66, v66
	v_rcp_f32_e32 v67, v67
	v_rcp_f32_e32 v68, v68
	v_rcp_f32_e32 v69, v69
	v_rcp_f32_e32 v70, v70
	v_rcp_f32_e32 v71, v71
	v_rcp_f32_e32 v72, v72
	v_rcp_f32_e32 v73, v73
	v_rcp_f32_e32 v74, v74
	v_rcp_f32_e32 v75, v75
	v_rcp_f32_e32 v76, v76
	v_rcp_f32_e32 v77, v77
	v_rcp_f32_e32 v78, v78
	v_rcp_f32_e32 v79, v79
	v_rcp_f32_e32 v80, v80
	v_rcp_f32_e32 v81, v81
	v_mul_f32_e32 v66, v1, v66
	v_mul_f32_e32 v67, v1, v67
	v_mul_f32_e32 v68, v1, v68
	v_mul_f32_e32 v69, v1, v69
	v_mul_f32_e32 v70, v1, v70
	v_mul_f32_e32 v71, v1, v71
	v_mul_f32_e32 v72, v1, v72
	v_mul_f32_e32 v73, v1, v73
	v_mul_f32_e32 v74, v1, v74
	v_mul_f32_e32 v75, v1, v75
	v_mul_f32_e32 v76, v1, v76
	v_mul_f32_e32 v77, v1, v77
	v_mul_f32_e32 v78, v1, v78
	v_mul_f32_e32 v79, v1, v79
	v_mul_f32_e32 v80, v1, v80
	v_mul_f32_e32 v81, v1, v81
	s_waitcnt vmcnt(15)
	v_fma_f32 v106, -v50, v66, v106
	v_fma_f32 v107, -v34, v66, v107
	v_fma_f32 v108, -v18, v66, v108
	v_fma_f32 v109, -v2, v66, v109
	v_mul_f32_e32 v204, 0x3f4ccccd, v204
	v_mul_f32_e32 v205, 0x3f4ccccd, v205
	v_mul_f32_e32 v206, 0x3f4ccccd, v206
	v_mul_f32_e32 v207, 0x3f4ccccd, v207
	v_mul_f32_e32 v66, v106, v106
	v_fmac_f32_e32 v66, v107, v107
	v_fmac_f32_e32 v66, v108, v108
	v_fmac_f32_e32 v66, v109, v109
	s_waitcnt vmcnt(14)
	v_fma_f32 v110, -v51, v67, v110
	v_fma_f32 v111, -v35, v67, v111
	v_fma_f32 v112, -v19, v67, v112
	v_fma_f32 v113, -v3, v67, v113
	v_mul_f32_e32 v67, v110, v110
	v_fmac_f32_e32 v67, v111, v111
	v_fmac_f32_e32 v67, v112, v112
	v_fmac_f32_e32 v67, v113, v113
	s_waitcnt vmcnt(13)
	v_fma_f32 v114, -v52, v68, v114
	v_fma_f32 v115, -v36, v68, v115
	v_fma_f32 v116, -v20, v68, v116
	v_fma_f32 v117, -v4, v68, v117
	v_mul_f32_e32 v68, v114, v114
	v_fmac_f32_e32 v68, v115, v115
	v_fmac_f32_e32 v68, v116, v116
	v_fmac_f32_e32 v68, v117, v117
	s_waitcnt vmcnt(12)
	v_fma_f32 v118, -v53, v69, v118
	v_fma_f32 v119, -v37, v69, v119
	v_fma_f32 v120, -v21, v69, v120
	v_fma_f32 v121, -v5, v69, v121
	v_mul_f32_e32 v69, v118, v118
	v_fmac_f32_e32 v69, v119, v119
	v_fmac_f32_e32 v69, v120, v120
	v_fmac_f32_e32 v69, v121, v121
	s_waitcnt vmcnt(11)
	v_fma_f32 v122, -v54, v70, v122
	v_fma_f32 v123, -v38, v70, v123
	v_fma_f32 v124, -v22, v70, v124
	v_fma_f32 v125, -v6, v70, v125
	v_mul_f32_e32 v70, v122, v122
	v_fmac_f32_e32 v70, v123, v123
	v_fmac_f32_e32 v70, v124, v124
	v_fmac_f32_e32 v70, v125, v125
	s_waitcnt vmcnt(10)
	v_fma_f32 v126, -v55, v71, v126
	v_fma_f32 v127, -v39, v71, v127
	v_fma_f32 v128, -v23, v71, v128
	v_fma_f32 v129, -v7, v71, v129
	v_mul_f32_e32 v71, v126, v126
	v_fmac_f32_e32 v71, v127, v127
	v_fmac_f32_e32 v71, v128, v128
	v_fmac_f32_e32 v71, v129, v129
	s_waitcnt vmcnt(9)
	v_fma_f32 v130, -v56, v72, v130
	v_fma_f32 v131, -v40, v72, v131
	v_fma_f32 v132, -v24, v72, v132
	v_fma_f32 v133, -v8, v72, v133
	v_mul_f32_e32 v72, v130, v130
	v_fmac_f32_e32 v72, v131, v131
	v_fmac_f32_e32 v72, v132, v132
	v_fmac_f32_e32 v72, v133, v133
	s_waitcnt vmcnt(8)
	v_fma_f32 v134, -v57, v73, v134
	v_fma_f32 v135, -v41, v73, v135
	v_fma_f32 v136, -v25, v73, v136
	v_fma_f32 v137, -v9, v73, v137
	v_mul_f32_e32 v73, v134, v134
	v_fmac_f32_e32 v73, v135, v135
	v_fmac_f32_e32 v73, v136, v136
	v_fmac_f32_e32 v73, v137, v137
	s_waitcnt vmcnt(7)
	v_fma_f32 v138, -v58, v74, v138
	v_fma_f32 v139, -v42, v74, v139
	v_fma_f32 v140, -v26, v74, v140
	v_fma_f32 v141, -v10, v74, v141
	v_mul_f32_e32 v74, v138, v138
	v_fmac_f32_e32 v74, v139, v139
	v_fmac_f32_e32 v74, v140, v140
	v_fmac_f32_e32 v74, v141, v141
	s_waitcnt vmcnt(6)
	v_fma_f32 v142, -v59, v75, v142
	v_fma_f32 v143, -v43, v75, v143
	v_fma_f32 v144, -v27, v75, v144
	v_fma_f32 v145, -v11, v75, v145
	v_mul_f32_e32 v75, v142, v142
	v_fmac_f32_e32 v75, v143, v143
	v_fmac_f32_e32 v75, v144, v144
	v_fmac_f32_e32 v75, v145, v145
	s_waitcnt vmcnt(5)
	v_fma_f32 v146, -v60, v76, v146
	v_fma_f32 v147, -v44, v76, v147
	v_fma_f32 v148, -v28, v76, v148
	v_fma_f32 v149, -v12, v76, v149
	v_mul_f32_e32 v76, v146, v146
	v_fmac_f32_e32 v76, v147, v147
	v_fmac_f32_e32 v76, v148, v148
	v_fmac_f32_e32 v76, v149, v149
	s_waitcnt vmcnt(4)
	v_fma_f32 v150, -v61, v77, v150
	v_fma_f32 v151, -v45, v77, v151
	v_fma_f32 v152, -v29, v77, v152
	v_fma_f32 v153, -v13, v77, v153
	v_mul_f32_e32 v77, v150, v150
	v_fmac_f32_e32 v77, v151, v151
	v_fmac_f32_e32 v77, v152, v152
	v_fmac_f32_e32 v77, v153, v153
	s_waitcnt vmcnt(3)
	v_fma_f32 v154, -v62, v78, v154
	v_fma_f32 v155, -v46, v78, v155
	v_fma_f32 v156, -v30, v78, v156
	v_fma_f32 v157, -v14, v78, v157
	v_mul_f32_e32 v78, v154, v154
	v_fmac_f32_e32 v78, v155, v155
	v_fmac_f32_e32 v78, v156, v156
	v_fmac_f32_e32 v78, v157, v157
	s_waitcnt vmcnt(2)
	v_fma_f32 v176, -v63, v79, v176
	v_fma_f32 v177, -v47, v79, v177
	v_fma_f32 v178, -v31, v79, v178
	v_fma_f32 v179, -v15, v79, v179
	v_mul_f32_e32 v79, v176, v176
	v_fmac_f32_e32 v79, v177, v177
	v_fmac_f32_e32 v79, v178, v178
	v_fmac_f32_e32 v79, v179, v179
	s_waitcnt vmcnt(1)
	v_fma_f32 v180, -v64, v80, v180
	v_fma_f32 v181, -v48, v80, v181
	v_fma_f32 v182, -v32, v80, v182
	v_fma_f32 v183, -v16, v80, v183
	v_mul_f32_e32 v80, v180, v180
	v_fmac_f32_e32 v80, v181, v181
	v_fmac_f32_e32 v80, v182, v182
	v_fmac_f32_e32 v80, v183, v183
	s_waitcnt vmcnt(0)
	v_fma_f32 v184, -v65, v81, v184
	v_fma_f32 v185, -v49, v81, v185
	v_fma_f32 v186, -v33, v81, v186
	v_fma_f32 v187, -v17, v81, v187
	v_mul_f32_e32 v81, v184, v184
	v_fmac_f32_e32 v81, v185, v185
	v_fmac_f32_e32 v81, v186, v186
	v_fmac_f32_e32 v81, v187, v187
	v_add_f32_dpp v66, v66, v66 quad_perm:[1,0,3,2] row_mask:0xf bank_mask:0xf
	v_add_f32_dpp v67, v67, v67 quad_perm:[1,0,3,2] row_mask:0xf bank_mask:0xf
	v_add_f32_dpp v68, v68, v68 quad_perm:[1,0,3,2] row_mask:0xf bank_mask:0xf
	v_add_f32_dpp v69, v69, v69 quad_perm:[1,0,3,2] row_mask:0xf bank_mask:0xf
	v_add_f32_dpp v70, v70, v70 quad_perm:[1,0,3,2] row_mask:0xf bank_mask:0xf
	v_add_f32_dpp v71, v71, v71 quad_perm:[1,0,3,2] row_mask:0xf bank_mask:0xf
	v_add_f32_dpp v72, v72, v72 quad_perm:[1,0,3,2] row_mask:0xf bank_mask:0xf
	v_add_f32_dpp v73, v73, v73 quad_perm:[1,0,3,2] row_mask:0xf bank_mask:0xf
	v_add_f32_dpp v74, v74, v74 quad_perm:[1,0,3,2] row_mask:0xf bank_mask:0xf
	v_add_f32_dpp v75, v75, v75 quad_perm:[1,0,3,2] row_mask:0xf bank_mask:0xf
	v_add_f32_dpp v76, v76, v76 quad_perm:[1,0,3,2] row_mask:0xf bank_mask:0xf
	v_add_f32_dpp v77, v77, v77 quad_perm:[1,0,3,2] row_mask:0xf bank_mask:0xf
	v_add_f32_dpp v78, v78, v78 quad_perm:[1,0,3,2] row_mask:0xf bank_mask:0xf
	v_add_f32_dpp v79, v79, v79 quad_perm:[1,0,3,2] row_mask:0xf bank_mask:0xf
	v_add_f32_dpp v80, v80, v80 quad_perm:[1,0,3,2] row_mask:0xf bank_mask:0xf
	v_add_f32_dpp v81, v81, v81 quad_perm:[1,0,3,2] row_mask:0xf bank_mask:0xf
	v_add_f32_dpp v66, v66, v66 quad_perm:[2,3,0,1] row_mask:0xf bank_mask:0xf
	v_add_f32_dpp v67, v67, v67 quad_perm:[2,3,0,1] row_mask:0xf bank_mask:0xf
	v_add_f32_dpp v68, v68, v68 quad_perm:[2,3,0,1] row_mask:0xf bank_mask:0xf
	v_add_f32_dpp v69, v69, v69 quad_perm:[2,3,0,1] row_mask:0xf bank_mask:0xf
	v_add_f32_dpp v70, v70, v70 quad_perm:[2,3,0,1] row_mask:0xf bank_mask:0xf
	v_add_f32_dpp v71, v71, v71 quad_perm:[2,3,0,1] row_mask:0xf bank_mask:0xf
	v_add_f32_dpp v72, v72, v72 quad_perm:[2,3,0,1] row_mask:0xf bank_mask:0xf
	v_add_f32_dpp v73, v73, v73 quad_perm:[2,3,0,1] row_mask:0xf bank_mask:0xf
	v_add_f32_dpp v74, v74, v74 quad_perm:[2,3,0,1] row_mask:0xf bank_mask:0xf
	v_add_f32_dpp v75, v75, v75 quad_perm:[2,3,0,1] row_mask:0xf bank_mask:0xf
	v_add_f32_dpp v76, v76, v76 quad_perm:[2,3,0,1] row_mask:0xf bank_mask:0xf
	v_add_f32_dpp v77, v77, v77 quad_perm:[2,3,0,1] row_mask:0xf bank_mask:0xf
	v_add_f32_dpp v78, v78, v78 quad_perm:[2,3,0,1] row_mask:0xf bank_mask:0xf
	v_add_f32_dpp v79, v79, v79 quad_perm:[2,3,0,1] row_mask:0xf bank_mask:0xf
	v_add_f32_dpp v80, v80, v80 quad_perm:[2,3,0,1] row_mask:0xf bank_mask:0xf
	v_add_f32_dpp v81, v81, v81 quad_perm:[2,3,0,1] row_mask:0xf bank_mask:0xf
	v_add_f32_dpp v66, v66, v66 row_half_mirror row_mask:0xf bank_mask:0xf
	v_add_f32_dpp v67, v67, v67 row_half_mirror row_mask:0xf bank_mask:0xf
	v_add_f32_dpp v68, v68, v68 row_half_mirror row_mask:0xf bank_mask:0xf
	v_add_f32_dpp v69, v69, v69 row_half_mirror row_mask:0xf bank_mask:0xf
	v_add_f32_dpp v70, v70, v70 row_half_mirror row_mask:0xf bank_mask:0xf
	v_add_f32_dpp v71, v71, v71 row_half_mirror row_mask:0xf bank_mask:0xf
	v_add_f32_dpp v72, v72, v72 row_half_mirror row_mask:0xf bank_mask:0xf
	v_add_f32_dpp v73, v73, v73 row_half_mirror row_mask:0xf bank_mask:0xf
	v_add_f32_dpp v74, v74, v74 row_half_mirror row_mask:0xf bank_mask:0xf
	v_add_f32_dpp v75, v75, v75 row_half_mirror row_mask:0xf bank_mask:0xf
	v_add_f32_dpp v76, v76, v76 row_half_mirror row_mask:0xf bank_mask:0xf
	v_add_f32_dpp v77, v77, v77 row_half_mirror row_mask:0xf bank_mask:0xf
	v_add_f32_dpp v78, v78, v78 row_half_mirror row_mask:0xf bank_mask:0xf
	v_add_f32_dpp v79, v79, v79 row_half_mirror row_mask:0xf bank_mask:0xf
	v_add_f32_dpp v80, v80, v80 row_half_mirror row_mask:0xf bank_mask:0xf
	v_add_f32_dpp v81, v81, v81 row_half_mirror row_mask:0xf bank_mask:0xf
	v_add_f32_dpp v66, v66, v66 row_mirror row_mask:0xf bank_mask:0xf
	v_add_f32_dpp v67, v67, v67 row_mirror row_mask:0xf bank_mask:0xf
	v_add_f32_dpp v68, v68, v68 row_mirror row_mask:0xf bank_mask:0xf
	v_add_f32_dpp v69, v69, v69 row_mirror row_mask:0xf bank_mask:0xf
	v_add_f32_dpp v70, v70, v70 row_mirror row_mask:0xf bank_mask:0xf
	v_add_f32_dpp v71, v71, v71 row_mirror row_mask:0xf bank_mask:0xf
	v_add_f32_dpp v72, v72, v72 row_mirror row_mask:0xf bank_mask:0xf
	v_add_f32_dpp v73, v73, v73 row_mirror row_mask:0xf bank_mask:0xf
	v_add_f32_dpp v74, v74, v74 row_mirror row_mask:0xf bank_mask:0xf
	v_add_f32_dpp v75, v75, v75 row_mirror row_mask:0xf bank_mask:0xf
	v_add_f32_dpp v76, v76, v76 row_mirror row_mask:0xf bank_mask:0xf
	v_add_f32_dpp v77, v77, v77 row_mirror row_mask:0xf bank_mask:0xf
	v_add_f32_dpp v78, v78, v78 row_mirror row_mask:0xf bank_mask:0xf
	v_add_f32_dpp v79, v79, v79 row_mirror row_mask:0xf bank_mask:0xf
	v_add_f32_dpp v80, v80, v80 row_mirror row_mask:0xf bank_mask:0xf
	v_add_f32_dpp v81, v81, v81 row_mirror row_mask:0xf bank_mask:0xf
	ds_bpermute_b32 v188, v208, v66
	ds_bpermute_b32 v189, v208, v67
	ds_bpermute_b32 v190, v208, v68
	ds_bpermute_b32 v191, v208, v69
	ds_bpermute_b32 v192, v208, v70
	ds_bpermute_b32 v193, v208, v71
	ds_bpermute_b32 v194, v208, v72
	ds_bpermute_b32 v195, v208, v73
	ds_bpermute_b32 v196, v208, v74
	ds_bpermute_b32 v197, v208, v75
	ds_bpermute_b32 v198, v208, v76
	ds_bpermute_b32 v199, v208, v77
	ds_bpermute_b32 v200, v208, v78
	ds_bpermute_b32 v201, v208, v79
	ds_bpermute_b32 v202, v208, v80
	ds_bpermute_b32 v203, v208, v81
	s_waitcnt lgkmcnt(0)
	v_add_f32_e32 v66, v66, v188
	v_add_f32_e32 v67, v67, v189
	v_add_f32_e32 v68, v68, v190
	v_add_f32_e32 v69, v69, v191
	v_add_f32_e32 v70, v70, v192
	v_add_f32_e32 v71, v71, v193
	v_add_f32_e32 v72, v72, v194
	v_add_f32_e32 v73, v73, v195
	v_add_f32_e32 v74, v74, v196
	v_add_f32_e32 v75, v75, v197
	v_add_f32_e32 v76, v76, v198
	v_add_f32_e32 v77, v77, v199
	v_add_f32_e32 v78, v78, v200
	v_add_f32_e32 v79, v79, v201
	v_add_f32_e32 v80, v80, v202
	v_add_f32_e32 v81, v81, v203
	v_fmamk_f32 v66, v66, 0x3c000000, v172
	v_fmamk_f32 v67, v67, 0x3c000000, v172
	v_fmamk_f32 v68, v68, 0x3c000000, v172
	v_fmamk_f32 v69, v69, 0x3c000000, v172
	v_fmamk_f32 v70, v70, 0x3c000000, v172
	v_fmamk_f32 v71, v71, 0x3c000000, v172
	v_fmamk_f32 v72, v72, 0x3c000000, v172
	v_fmamk_f32 v73, v73, 0x3c000000, v172
	v_fmamk_f32 v74, v74, 0x3c000000, v172
	v_fmamk_f32 v75, v75, 0x3c000000, v172
	v_fmamk_f32 v76, v76, 0x3c000000, v172
	v_fmamk_f32 v77, v77, 0x3c000000, v172
	v_fmamk_f32 v78, v78, 0x3c000000, v172
	v_fmamk_f32 v79, v79, 0x3c000000, v172
	v_fmamk_f32 v80, v80, 0x3c000000, v172
	v_fmamk_f32 v81, v81, 0x3c000000, v172
	v_rsq_f32_e32 v66, v66
	v_rsq_f32_e32 v67, v67
	v_rsq_f32_e32 v68, v68
	v_rsq_f32_e32 v69, v69
	v_rsq_f32_e32 v70, v70
	v_rsq_f32_e32 v71, v71
	v_rsq_f32_e32 v72, v72
	v_rsq_f32_e32 v73, v73
	v_rsq_f32_e32 v74, v74
	v_rsq_f32_e32 v75, v75
	v_rsq_f32_e32 v76, v76
	v_rsq_f32_e32 v77, v77
	v_rsq_f32_e32 v78, v78
	v_rsq_f32_e32 v79, v79
	v_rsq_f32_e32 v80, v80
	v_rsq_f32_e32 v81, v81
	s_nop 0
	s_mov_b32 s96, 0xaaaaaaaa
	s_mov_b32 s97, 0xaaaaaaaa
	s_mov_b32 s98, 0xcccccccc
	s_mov_b32 s99, 0xcccccccc
	v_mov_b32_e32 v202, 0x5040100
	v_mov_b32_e32 v203, 0x3020706
	v_cndmask_b32_e64 v202, v202, v203, s[96:97]
	v_and_b32_e32 v209, 3, v163
	v_lshl_add_u32 v209, v164, 2, v209
	v_add_u32_e32 v209, v175, v209
	v_lshlrev_b32_e32 v209, 12, v209
	v_lshrrev_b32_e32 v210, 2, v163
	v_lshl_add_u32 v209, v210, 3, v209
	v_mul_f32_e32 v198, v106, v66
	v_mul_f32_e32 v199, v110, v67
	v_mul_f32_e32 v200, v114, v68
	v_mul_f32_e32 v201, v118, v69
	v_mul_f32_e32 v198, v204, v198
	v_mul_f32_e32 v199, v204, v199
	v_mul_f32_e32 v200, v204, v200
	v_mul_f32_e32 v201, v204, v201
	v_cvt_pk_bf16_f32 v188, v198, v199
	v_cvt_pk_bf16_f32 v189, v200, v201
	s_nop 0
	v_mov_b32_dpp v190, v188 quad_perm:[1,0,3,2] row_mask:0xf bank_mask:0xf
	v_mov_b32_dpp v191, v189 quad_perm:[1,0,3,2] row_mask:0xf bank_mask:0xf
	v_perm_b32 v192, v190, v188, v202
	v_perm_b32 v193, v191, v189, v202
	v_cndmask_b32_e64 v194, v193, v192, s[98:99]
	s_nop 1
	v_mov_b32_dpp v195, v194 quad_perm:[2,3,0,1] row_mask:0xf bank_mask:0xf
	v_cndmask_b32_e64 v196, v192, v195, s[98:99]
	v_cndmask_b32_e64 v197, v195, v193, s[98:99]
	global_store_dwordx2 v209, v[196:197], s[100:101] offset:2048
	v_mul_f32_e32 v198, v107, v66
	v_mul_f32_e32 v199, v111, v67
	v_mul_f32_e32 v200, v115, v68
	v_mul_f32_e32 v201, v119, v69
	v_mul_f32_e32 v198, v205, v198
	v_mul_f32_e32 v199, v205, v199
	v_mul_f32_e32 v200, v205, v200
	v_mul_f32_e32 v201, v205, v201
	v_cvt_pk_bf16_f32 v188, v198, v199
	v_cvt_pk_bf16_f32 v189, v200, v201
	s_nop 0
	v_mov_b32_dpp v190, v188 quad_perm:[1,0,3,2] row_mask:0xf bank_mask:0xf
	v_mov_b32_dpp v191, v189 quad_perm:[1,0,3,2] row_mask:0xf bank_mask:0xf
	v_perm_b32 v192, v190, v188, v202
	v_perm_b32 v193, v191, v189, v202
	v_cndmask_b32_e64 v194, v193, v192, s[98:99]
	s_nop 1
	v_mov_b32_dpp v195, v194 quad_perm:[2,3,0,1] row_mask:0xf bank_mask:0xf
	v_cndmask_b32_e64 v216, v192, v195, s[98:99]
	v_cndmask_b32_e64 v217, v195, v193, s[98:99]
	global_store_dwordx2 v209, v[216:217], s[100:101] offset:2112
	v_mul_f32_e32 v198, v108, v66
	v_mul_f32_e32 v199, v112, v67
	v_mul_f32_e32 v200, v116, v68
	v_mul_f32_e32 v201, v120, v69
	v_mul_f32_e32 v198, v206, v198
	v_mul_f32_e32 v199, v206, v199
	v_mul_f32_e32 v200, v206, v200
	v_mul_f32_e32 v201, v206, v201
	v_cvt_pk_bf16_f32 v188, v198, v199
	v_cvt_pk_bf16_f32 v189, v200, v201
	s_nop 0
	v_mov_b32_dpp v190, v188 quad_perm:[1,0,3,2] row_mask:0xf bank_mask:0xf
	v_mov_b32_dpp v191, v189 quad_perm:[1,0,3,2] row_mask:0xf bank_mask:0xf
	v_perm_b32 v192, v190, v188, v202
	v_perm_b32 v193, v191, v189, v202
	v_cndmask_b32_e64 v194, v193, v192, s[98:99]
	s_nop 1
	v_mov_b32_dpp v195, v194 quad_perm:[2,3,0,1] row_mask:0xf bank_mask:0xf
	v_cndmask_b32_e64 v196, v192, v195, s[98:99]
	v_cndmask_b32_e64 v197, v195, v193, s[98:99]
	global_store_dwordx2 v209, v[196:197], s[100:101] offset:2176
	v_mul_f32_e32 v198, v109, v66
	v_mul_f32_e32 v199, v113, v67
	v_mul_f32_e32 v200, v117, v68
	v_mul_f32_e32 v201, v121, v69
	v_mul_f32_e32 v198, v207, v198
	v_mul_f32_e32 v199, v207, v199
	v_mul_f32_e32 v200, v207, v200
	v_mul_f32_e32 v201, v207, v201
	v_cvt_pk_bf16_f32 v188, v198, v199
	v_cvt_pk_bf16_f32 v189, v200, v201
	s_nop 0
	v_mov_b32_dpp v190, v188 quad_perm:[1,0,3,2] row_mask:0xf bank_mask:0xf
	v_mov_b32_dpp v191, v189 quad_perm:[1,0,3,2] row_mask:0xf bank_mask:0xf
	v_perm_b32 v192, v190, v188, v202
	v_perm_b32 v193, v191, v189, v202
	v_cndmask_b32_e64 v194, v193, v192, s[98:99]
	s_nop 1
	v_mov_b32_dpp v195, v194 quad_perm:[2,3,0,1] row_mask:0xf bank_mask:0xf
	v_cndmask_b32_e64 v216, v192, v195, s[98:99]
	v_cndmask_b32_e64 v217, v195, v193, s[98:99]
	global_store_dwordx2 v209, v[216:217], s[100:101] offset:2240
	v_add_u32_e32 v210, 0x8000, v209
	v_mul_f32_e32 v198, v122, v70
	v_mul_f32_e32 v199, v126, v71
	v_mul_f32_e32 v200, v130, v72
	v_mul_f32_e32 v201, v134, v73
	v_mul_f32_e32 v198, v204, v198
	v_mul_f32_e32 v199, v204, v199
	v_mul_f32_e32 v200, v204, v200
	v_mul_f32_e32 v201, v204, v201
	v_cvt_pk_bf16_f32 v188, v198, v199
	v_cvt_pk_bf16_f32 v189, v200, v201
	s_nop 0
	v_mov_b32_dpp v190, v188 quad_perm:[1,0,3,2] row_mask:0xf bank_mask:0xf
	v_mov_b32_dpp v191, v189 quad_perm:[1,0,3,2] row_mask:0xf bank_mask:0xf
	v_perm_b32 v192, v190, v188, v202
	v_perm_b32 v193, v191, v189, v202
	v_cndmask_b32_e64 v194, v193, v192, s[98:99]
	s_nop 1
	v_mov_b32_dpp v195, v194 quad_perm:[2,3,0,1] row_mask:0xf bank_mask:0xf
	v_cndmask_b32_e64 v196, v192, v195, s[98:99]
	v_cndmask_b32_e64 v197, v195, v193, s[98:99]
	global_store_dwordx2 v210, v[196:197], s[100:101] offset:2048
	v_mul_f32_e32 v198, v123, v70
	v_mul_f32_e32 v199, v127, v71
	v_mul_f32_e32 v200, v131, v72
	v_mul_f32_e32 v201, v135, v73
	v_mul_f32_e32 v198, v205, v198
	v_mul_f32_e32 v199, v205, v199
	v_mul_f32_e32 v200, v205, v200
	v_mul_f32_e32 v201, v205, v201
	v_cvt_pk_bf16_f32 v188, v198, v199
	v_cvt_pk_bf16_f32 v189, v200, v201
	s_nop 0
	v_mov_b32_dpp v190, v188 quad_perm:[1,0,3,2] row_mask:0xf bank_mask:0xf
	v_mov_b32_dpp v191, v189 quad_perm:[1,0,3,2] row_mask:0xf bank_mask:0xf
	v_perm_b32 v192, v190, v188, v202
	v_perm_b32 v193, v191, v189, v202
	v_cndmask_b32_e64 v194, v193, v192, s[98:99]
	s_nop 1
	v_mov_b32_dpp v195, v194 quad_perm:[2,3,0,1] row_mask:0xf bank_mask:0xf
	v_cndmask_b32_e64 v216, v192, v195, s[98:99]
	v_cndmask_b32_e64 v217, v195, v193, s[98:99]
	global_store_dwordx2 v210, v[216:217], s[100:101] offset:2112
	v_mul_f32_e32 v198, v124, v70
	v_mul_f32_e32 v199, v128, v71
	v_mul_f32_e32 v200, v132, v72
	v_mul_f32_e32 v201, v136, v73
	v_mul_f32_e32 v198, v206, v198
	v_mul_f32_e32 v199, v206, v199
	v_mul_f32_e32 v200, v206, v200
	v_mul_f32_e32 v201, v206, v201
	v_cvt_pk_bf16_f32 v188, v198, v199
	v_cvt_pk_bf16_f32 v189, v200, v201
	s_nop 0
	v_mov_b32_dpp v190, v188 quad_perm:[1,0,3,2] row_mask:0xf bank_mask:0xf
	v_mov_b32_dpp v191, v189 quad_perm:[1,0,3,2] row_mask:0xf bank_mask:0xf
	v_perm_b32 v192, v190, v188, v202
	v_perm_b32 v193, v191, v189, v202
	v_cndmask_b32_e64 v194, v193, v192, s[98:99]
	s_nop 1
	v_mov_b32_dpp v195, v194 quad_perm:[2,3,0,1] row_mask:0xf bank_mask:0xf
	v_cndmask_b32_e64 v196, v192, v195, s[98:99]
	v_cndmask_b32_e64 v197, v195, v193, s[98:99]
	global_store_dwordx2 v210, v[196:197], s[100:101] offset:2176
	v_mul_f32_e32 v198, v125, v70
	v_mul_f32_e32 v199, v129, v71
	v_mul_f32_e32 v200, v133, v72
	v_mul_f32_e32 v201, v137, v73
	v_mul_f32_e32 v198, v207, v198
	v_mul_f32_e32 v199, v207, v199
	v_mul_f32_e32 v200, v207, v200
	v_mul_f32_e32 v201, v207, v201
	v_cvt_pk_bf16_f32 v188, v198, v199
	v_cvt_pk_bf16_f32 v189, v200, v201
	s_nop 0
	v_mov_b32_dpp v190, v188 quad_perm:[1,0,3,2] row_mask:0xf bank_mask:0xf
	v_mov_b32_dpp v191, v189 quad_perm:[1,0,3,2] row_mask:0xf bank_mask:0xf
	v_perm_b32 v192, v190, v188, v202
	v_perm_b32 v193, v191, v189, v202
	v_cndmask_b32_e64 v194, v193, v192, s[98:99]
	s_nop 1
	v_mov_b32_dpp v195, v194 quad_perm:[2,3,0,1] row_mask:0xf bank_mask:0xf
	v_cndmask_b32_e64 v216, v192, v195, s[98:99]
	v_cndmask_b32_e64 v217, v195, v193, s[98:99]
	global_store_dwordx2 v210, v[216:217], s[100:101] offset:2240
	v_add_u32_e32 v210, 0x10000, v209
	v_mul_f32_e32 v198, v138, v74
	v_mul_f32_e32 v199, v142, v75
	v_mul_f32_e32 v200, v146, v76
	v_mul_f32_e32 v201, v150, v77
	v_mul_f32_e32 v198, v204, v198
	v_mul_f32_e32 v199, v204, v199
	v_mul_f32_e32 v200, v204, v200
	v_mul_f32_e32 v201, v204, v201
	v_cvt_pk_bf16_f32 v188, v198, v199
	v_cvt_pk_bf16_f32 v189, v200, v201
	s_nop 0
	v_mov_b32_dpp v190, v188 quad_perm:[1,0,3,2] row_mask:0xf bank_mask:0xf
	v_mov_b32_dpp v191, v189 quad_perm:[1,0,3,2] row_mask:0xf bank_mask:0xf
	v_perm_b32 v192, v190, v188, v202
	v_perm_b32 v193, v191, v189, v202
	v_cndmask_b32_e64 v194, v193, v192, s[98:99]
	s_nop 1
	v_mov_b32_dpp v195, v194 quad_perm:[2,3,0,1] row_mask:0xf bank_mask:0xf
	v_cndmask_b32_e64 v196, v192, v195, s[98:99]
	v_cndmask_b32_e64 v197, v195, v193, s[98:99]
	global_store_dwordx2 v210, v[196:197], s[100:101] offset:2048
	v_mul_f32_e32 v198, v139, v74
	v_mul_f32_e32 v199, v143, v75
	v_mul_f32_e32 v200, v147, v76
	v_mul_f32_e32 v201, v151, v77
	v_mul_f32_e32 v198, v205, v198
	v_mul_f32_e32 v199, v205, v199
	v_mul_f32_e32 v200, v205, v200
	v_mul_f32_e32 v201, v205, v201
	v_cvt_pk_bf16_f32 v188, v198, v199
	v_cvt_pk_bf16_f32 v189, v200, v201
	s_nop 0
	v_mov_b32_dpp v190, v188 quad_perm:[1,0,3,2] row_mask:0xf bank_mask:0xf
	v_mov_b32_dpp v191, v189 quad_perm:[1,0,3,2] row_mask:0xf bank_mask:0xf
	v_perm_b32 v192, v190, v188, v202
	v_perm_b32 v193, v191, v189, v202
	v_cndmask_b32_e64 v194, v193, v192, s[98:99]
	s_nop 1
	v_mov_b32_dpp v195, v194 quad_perm:[2,3,0,1] row_mask:0xf bank_mask:0xf
	v_cndmask_b32_e64 v216, v192, v195, s[98:99]
	v_cndmask_b32_e64 v217, v195, v193, s[98:99]
	global_store_dwordx2 v210, v[216:217], s[100:101] offset:2112
	v_mul_f32_e32 v198, v140, v74
	v_mul_f32_e32 v199, v144, v75
	v_mul_f32_e32 v200, v148, v76
	v_mul_f32_e32 v201, v152, v77
	v_mul_f32_e32 v198, v206, v198
	v_mul_f32_e32 v199, v206, v199
	v_mul_f32_e32 v200, v206, v200
	v_mul_f32_e32 v201, v206, v201
	v_cvt_pk_bf16_f32 v188, v198, v199
	v_cvt_pk_bf16_f32 v189, v200, v201
	s_nop 0
	v_mov_b32_dpp v190, v188 quad_perm:[1,0,3,2] row_mask:0xf bank_mask:0xf
	v_mov_b32_dpp v191, v189 quad_perm:[1,0,3,2] row_mask:0xf bank_mask:0xf
	v_perm_b32 v192, v190, v188, v202
	v_perm_b32 v193, v191, v189, v202
	v_cndmask_b32_e64 v194, v193, v192, s[98:99]
	s_nop 1
	v_mov_b32_dpp v195, v194 quad_perm:[2,3,0,1] row_mask:0xf bank_mask:0xf
	v_cndmask_b32_e64 v196, v192, v195, s[98:99]
	v_cndmask_b32_e64 v197, v195, v193, s[98:99]
	global_store_dwordx2 v210, v[196:197], s[100:101] offset:2176
	v_mul_f32_e32 v198, v141, v74
	v_mul_f32_e32 v199, v145, v75
	v_mul_f32_e32 v200, v149, v76
	v_mul_f32_e32 v201, v153, v77
	v_mul_f32_e32 v198, v207, v198
	v_mul_f32_e32 v199, v207, v199
	v_mul_f32_e32 v200, v207, v200
	v_mul_f32_e32 v201, v207, v201
	v_cvt_pk_bf16_f32 v188, v198, v199
	v_cvt_pk_bf16_f32 v189, v200, v201
	s_nop 0
	v_mov_b32_dpp v190, v188 quad_perm:[1,0,3,2] row_mask:0xf bank_mask:0xf
	v_mov_b32_dpp v191, v189 quad_perm:[1,0,3,2] row_mask:0xf bank_mask:0xf
	v_perm_b32 v192, v190, v188, v202
	v_perm_b32 v193, v191, v189, v202
	v_cndmask_b32_e64 v194, v193, v192, s[98:99]
	s_nop 1
	v_mov_b32_dpp v195, v194 quad_perm:[2,3,0,1] row_mask:0xf bank_mask:0xf
	v_cndmask_b32_e64 v216, v192, v195, s[98:99]
	v_cndmask_b32_e64 v217, v195, v193, s[98:99]
	global_store_dwordx2 v210, v[216:217], s[100:101] offset:2240
	v_add_u32_e32 v210, 0x18000, v209
	v_mul_f32_e32 v198, v154, v78
	v_mul_f32_e32 v199, v176, v79
	v_mul_f32_e32 v200, v180, v80
	v_mul_f32_e32 v201, v184, v81
	v_mul_f32_e32 v198, v204, v198
	v_mul_f32_e32 v199, v204, v199
	v_mul_f32_e32 v200, v204, v200
	v_mul_f32_e32 v201, v204, v201
	v_cvt_pk_bf16_f32 v188, v198, v199
	v_cvt_pk_bf16_f32 v189, v200, v201
	s_nop 0
	v_mov_b32_dpp v190, v188 quad_perm:[1,0,3,2] row_mask:0xf bank_mask:0xf
	v_mov_b32_dpp v191, v189 quad_perm:[1,0,3,2] row_mask:0xf bank_mask:0xf
	v_perm_b32 v192, v190, v188, v202
	v_perm_b32 v193, v191, v189, v202
	v_cndmask_b32_e64 v194, v193, v192, s[98:99]
	s_nop 1
	v_mov_b32_dpp v195, v194 quad_perm:[2,3,0,1] row_mask:0xf bank_mask:0xf
	v_cndmask_b32_e64 v196, v192, v195, s[98:99]
	v_cndmask_b32_e64 v197, v195, v193, s[98:99]
	global_store_dwordx2 v210, v[196:197], s[100:101] offset:2048
	v_mul_f32_e32 v198, v155, v78
	v_mul_f32_e32 v199, v177, v79
	v_mul_f32_e32 v200, v181, v80
	v_mul_f32_e32 v201, v185, v81
	v_mul_f32_e32 v198, v205, v198
	v_mul_f32_e32 v199, v205, v199
	v_mul_f32_e32 v200, v205, v200
	v_mul_f32_e32 v201, v205, v201
	v_cvt_pk_bf16_f32 v188, v198, v199
	v_cvt_pk_bf16_f32 v189, v200, v201
	s_nop 0
	v_mov_b32_dpp v190, v188 quad_perm:[1,0,3,2] row_mask:0xf bank_mask:0xf
	v_mov_b32_dpp v191, v189 quad_perm:[1,0,3,2] row_mask:0xf bank_mask:0xf
	v_perm_b32 v192, v190, v188, v202
	v_perm_b32 v193, v191, v189, v202
	v_cndmask_b32_e64 v194, v193, v192, s[98:99]
	s_nop 1
	v_mov_b32_dpp v195, v194 quad_perm:[2,3,0,1] row_mask:0xf bank_mask:0xf
	v_cndmask_b32_e64 v216, v192, v195, s[98:99]
	v_cndmask_b32_e64 v217, v195, v193, s[98:99]
	global_store_dwordx2 v210, v[216:217], s[100:101] offset:2112
	v_mul_f32_e32 v198, v156, v78
	v_mul_f32_e32 v199, v178, v79
	v_mul_f32_e32 v200, v182, v80
	v_mul_f32_e32 v201, v186, v81
	v_mul_f32_e32 v198, v206, v198
	v_mul_f32_e32 v199, v206, v199
	v_mul_f32_e32 v200, v206, v200
	v_mul_f32_e32 v201, v206, v201
	v_cvt_pk_bf16_f32 v188, v198, v199
	v_cvt_pk_bf16_f32 v189, v200, v201
	s_nop 0
	v_mov_b32_dpp v190, v188 quad_perm:[1,0,3,2] row_mask:0xf bank_mask:0xf
	v_mov_b32_dpp v191, v189 quad_perm:[1,0,3,2] row_mask:0xf bank_mask:0xf
	v_perm_b32 v192, v190, v188, v202
	v_perm_b32 v193, v191, v189, v202
	v_cndmask_b32_e64 v194, v193, v192, s[98:99]
	s_nop 1
	v_mov_b32_dpp v195, v194 quad_perm:[2,3,0,1] row_mask:0xf bank_mask:0xf
	v_cndmask_b32_e64 v196, v192, v195, s[98:99]
	v_cndmask_b32_e64 v197, v195, v193, s[98:99]
	global_store_dwordx2 v210, v[196:197], s[100:101] offset:2176
	v_mul_f32_e32 v198, v157, v78
	v_mul_f32_e32 v199, v179, v79
	v_mul_f32_e32 v200, v183, v80
	v_mul_f32_e32 v201, v187, v81
	v_mul_f32_e32 v198, v207, v198
	v_mul_f32_e32 v199, v207, v199
	v_mul_f32_e32 v200, v207, v200
	v_mul_f32_e32 v201, v207, v201
	v_cvt_pk_bf16_f32 v188, v198, v199
	v_cvt_pk_bf16_f32 v189, v200, v201
	s_nop 0
	v_mov_b32_dpp v190, v188 quad_perm:[1,0,3,2] row_mask:0xf bank_mask:0xf
	v_mov_b32_dpp v191, v189 quad_perm:[1,0,3,2] row_mask:0xf bank_mask:0xf
	v_perm_b32 v192, v190, v188, v202
	v_perm_b32 v193, v191, v189, v202
	v_cndmask_b32_e64 v194, v193, v192, s[98:99]
	s_nop 1
	v_mov_b32_dpp v195, v194 quad_perm:[2,3,0,1] row_mask:0xf bank_mask:0xf
	v_cndmask_b32_e64 v216, v192, v195, s[98:99]
	v_cndmask_b32_e64 v217, v195, v193, s[98:99]
	global_store_dwordx2 v210, v[216:217], s[100:101] offset:2240
	s_cbranch_execnz .LBB0_335
